# baseline (speedup 1.0000x reference)
; __device__ __forceinline__ void phase_scan(const Params& p, int wid_s, char* shm) {
;   TID_DECL; const int slot = tid >> 8, q = tid & 255;
;   const int BUF_F = SCAN_CH * SCAN_STEP_F;
;   float* buf = (float*)shm + slot * (2 * BUF_F);
;   float* cst = (float*)shm + 4 * BUF_F + slot * 576;
;   float* ybuf = (float*)shm + 4 * BUF_F + 2 * 576 + slot * (2 * SCAN_CH * 64);
;   u16* Y = (u16*)(p.ws + OFF_Y);
;   const int rg = q >> 3, cg8 = q & 7;
;   for (int j0 = blockIdx.x; j0 < 256; j0 += gridDim.x) {
;     bool active; int dir, h, T, ts;
;     if (slot == 0) { active = true; dir = j0 >> 7; int r = j0 & 127; h = r & 15; T = 4096; ts = 8192 + (r >> 4) * 4096; }
;     else { active = j0 < 128; dir = (j0 >> 6) & 1; int r = j0 & 63; h = r & 15; T = 2048; ts = (r >> 4) * 2048; }
;     const int mynch = active ? (T / SCAN_CH) : 0;
;     __syncthreads();
;     if (active && q < 64) {
;       int n = q, col = h * 64 + n;
;       cst[0 * 64 + n] = p.shift_mu[col];
;       cst[1 * 64 + n] = p.shift_mu[3488 + col];
;       cst[2 * 64 + n] = p.shift_mu[1024 + col];
;       cst[3 * 64 + n] = p.shift_mu[3488 + 1024 + col];
;       cst[4 * 64 + n] = p.shift_mu[2048 + col];
;       cst[5 * 64 + n] = p.shift_mu[3488 + 2048 + col];
;       cst[6 * 64 + n] = p.k_k[col];
;       cst[7 * 64 + n] = p.k_a[col];
;       cst[8 * 64 + n] = p.r_k[col];
;     }
;     __syncthreads();
;     ScanLoads ld;
;     if (active) { scan_issue(p, ld, dir, T, ts, h, 0, q); scan_prep(p, ld, cst, buf, dir, T, ts, h, 0, q); }
;     __syncthreads();
;     v2f S0[4], S1[4];
; #pragma unroll
;     for (int c = 0; c < 4; ++c) { S0[c] = v2f{0.f, 0.f}; S1[c] = v2f{0.f, 0.f}; }
.LBB0_836:
	s_cmp_gt_i32 s96, 5
	s_cselect_b64 s[0:1], -1, 0
	s_cmp_lt_i32 s97, 5
	s_cselect_b64 s[2:3], -1, 0
	s_or_b64 s[0:1], s[0:1], s[2:3]
	s_and_b64 vcc, exec, s[0:1]
	s_cbranch_vccnz .LBB0_893
	s_cmp_lt_u32 s72, 0x100
	s_cbranch_scc1 .Lscan_noprio
	s_setprio 1
.Lscan_noprio:
	s_cmpk_gt_i32 s76, 0xff
	s_movk_i32 s0, 0xff
	v_mbcnt_lo_u32_b32 v2, -1, 0
	v_mbcnt_hi_u32_b32 v2, -1, v2
	s_cbranch_scc1 .LBB0_872
	s_and_b32 s1, s72, 0xffffffc0
	v_add_u32_e32 v3, s1, v2
	v_mov_b32_e32 v1, 64
	v_cmp_lt_u32_sdwa s[10:11], v3, v1 src0_sel:BYTE_0 src1_sel:DWORD
	v_mov_b32_e32 v1, 2
	v_ashrrev_i32_e32 v6, 8, v3
	s_movk_i32 s1, 0x900
	v_mov_b32_e32 v0, 0x18400
	v_lshlrev_b32_sdwa v104, v1, v3 dst_sel:DWORD dst_unused:UNUSED_PAD src0_sel:DWORD src1_sel:BYTE_0
	v_and_b32_e32 v1, 15, v2
	v_mad_i32_i24 v0, v6, s1, v0
	v_bfe_u32 v106, v3, 4, 4
	v_lshlrev_b32_e32 v4, 4, v1
	s_mov_b32 s4, 0xc200
	v_add_u32_e32 v105, v0, v104
	v_and_b32_e32 v108, 60, v104
	v_or_b32_e32 v110, v0, v4
	v_mul_u32_u24_e32 v0, 0x610, v106
	v_lshlrev_b32_e32 v8, 13, v6
	v_lshlrev_b32_e32 v109, 2, v1
	v_mad_i32_i24 v111, v6, s4, v0
	v_cmp_eq_u32_e64 s[8:9], 0, v1
	v_lshlrev_b32_e32 v0, 8, v106
	v_lshlrev_b32_e32 v1, 2, v108
	v_or3_b32 v0, v8, v0, v1
	v_add_u32_e32 v113, 0x19600, v0
	v_lshlrev_b32_e32 v0, 1, v108
	v_mov_b32_e32 v1, 0
	s_add_u32 s14, s30, 0x2be00000
	v_mul_i32_i24_e32 v7, 0xc200, v6
	v_add_u32_e32 v112, v111, v4
	v_lshl_add_u64 v[4:5], s[30:31], 0, v[0:1]
	s_addc_u32 s15, s31, 0
	v_and_b32_e32 v0, 7, v2
	s_add_u32 s16, s30, 0x12e00000
	v_lshl_or_b32 v114, v0, 5, v7
	v_and_b32_e32 v0, 0xf8, v3
	s_addc_u32 s17, s31, 0
	v_or_b32_e32 v2, v7, v0
	s_mov_b32 s12, 0
	s_mov_b64 s[2:3], 0x5e00000
	s_add_u32 s18, s30, 0x5680000
	v_add_u32_e32 v115, 0x500, v2
	v_mov_b32_e32 v2, 0x600
	v_cmp_lt_u32_e64 s[0:1], s0, v3
	v_not_b32_e32 v107, v106
	s_mov_b32 s13, 1.0
	v_lshl_add_u64 v[60:61], v[4:5], 0, s[2:3]
	s_addc_u32 s19, s31, 0
	v_mad_i32_i24 v116, v6, s4, v2
	v_or_b32_e32 v117, v8, v0
	s_mov_b32 s2, 0xa000
	s_movk_i32 s3, 0x1c00
	s_mov_b32 s44, 0x179abe15
	v_mov_b32_e32 v63, -1.0
	s_movk_i32 s45, 0x6100
	v_mov_b32_e32 v65, 1.0
	v_mov_b32_e32 v118, 0x5368d4a5
	s_mov_b32 s52, s76
	s_branch .LBB0_840

; __device__ __forceinline__ void ctr_barrier(unsigned* ctr, unsigned target, bool leader) {
;   asm volatile("s_waitcnt vmcnt(0)" ::: "memory");
;   __syncthreads();
;   if (leader) {
.LBB0_872:
	s_setprio 0
	s_cmp_lt_i32 s97, 6
	s_cbranch_scc1 .LBB0_893
	s_cmp_gt_u32 s72, 63
	s_mov_b64 s[4:5], 0
	s_cbranch_scc1 .LBB0_875
	v_mbcnt_lo_u32_b32 v0, -1, 0
	v_mbcnt_hi_u32_b32 v0, -1, v0
	s_nop 0
	v_cmp_eq_u32_e32 vcc, 0, v0
	s_and_b64 s[4:5], vcc, exec
